# baseline (speedup 1.0000x reference)
; __global__ void __launch_bounds__(NTHREADS) fwd_megakernel(Params p) {
;     ...
;   const int xcd = (int)(xb.x & 7u);
;   for (int rep_ = 0; rep_ < (DUP == 2 ? 2 : 1); ++rep_)
;   for (int st_ = 0; st_ < 8; ++st_) {
;     const int xq = (xcd + st_) & 7;
;     int pend = 0;
;     if (tid == 0) pend = (int)atomicAdd(&ctr[rep_ * 24 + xq], 1u);
.LBB0_1116:
	s_or_b64 exec, exec, s[2:3]
	s_add_u32 s2, s44, 0x2b400000
	v_writelane_b32 v241, s2, 38
	s_addc_u32 s2, s45, 0
	s_add_u32 s36, s44, 0x2f400000
	v_writelane_b32 v241, s2, 39
	s_addc_u32 s37, s45, 0
	s_add_u32 s33, s44, 0x15402c80
	v_readlane_b32 s69, v241, 35
	s_addc_u32 s47, s45, 0
	s_lshl_b32 s58, s69, 1
	s_add_u32 s59, s44, 0x15403c80
	s_barrier
	s_addc_u32 s60, s45, 0
	s_mov_b32 s39, 0
	v_mov_b32_e32 v181, 0
	s_movk_i32 s61, 0x5e00
	s_mov_b32 s62, 0x5040100
	s_mov_b32 s63, 0x3e0293ee
	s_mov_b32 s66, 0x41000000
	s_movk_i32 s67, 0x190
	s_mov_b64 s[40:41], 0x80000
	s_mov_b32 s68, 0x3dd53b94
	v_mov_b32_e32 v192, 0xff800000
	s_mov_b32 s70, 0
	s_mov_b32 s98, 0
	s_branch .LBB0_1118

; __global__ void __launch_bounds__(NTHREADS) fwd_megakernel(Params p) {
;     ...
;   for (int st_ = 0; st_ < 8; ++st_) {
;     const int xq = (xcd + st_) & 7;
;     int pend = 0;
;     if (tid == 0) pend = (int)atomicAdd(&ctr[rep_ * 24 + xq], 1u);
;     for (;;) {
;       __syncthreads();
;       if (tid == 0) s_item = pend;
;       __syncthreads();
;       const int n = s_item;
;       if (n >= 192) break;
;       if (tid == 0) pend = (int)atomicAdd(&ctr[rep_ * 24 + xq], 1u);
.LBB0_1118:
	v_readlane_b32 s2, v241, 35
	s_add_i32 s2, s70, s2
	s_and_b32 s38, s2, 7
	v_mov_b32_e32 v193, v181
	s_and_saveexec_b64 s[2:3], s[0:1]
	s_cbranch_execz .LBB0_1122
	s_cmp_lg_u32 s70, 1
	s_cbranch_scc1 .Lp4q_noprobe
	global_load_dword v242, v181, s[88:89] sc0 sc1
	global_load_dword v243, v181, s[88:89] offset:4 sc0 sc1
	global_load_dword v244, v181, s[88:89] offset:8 sc0 sc1
	global_load_dword v245, v181, s[88:89] offset:12 sc0 sc1
	global_load_dword v246, v181, s[88:89] offset:16 sc0 sc1
	global_load_dword v247, v181, s[88:89] offset:20 sc0 sc1
	global_load_dword v248, v181, s[88:89] offset:24 sc0 sc1
	global_load_dword v249, v181, s[88:89] offset:28 sc0 sc1
	s_mov_b32 s98, 0
	s_waitcnt vmcnt(0)
	v_readfirstlane_b32 s99, v242
	s_cmpk_ge_u32 s99, 0xc0
	s_cselect_b32 s99, 1, 0
	s_or_b32 s98, s98, s99
	v_readfirstlane_b32 s99, v243
	s_cmpk_ge_u32 s99, 0xc0
	s_cselect_b32 s99, 2, 0
	s_or_b32 s98, s98, s99
	v_readfirstlane_b32 s99, v244
	s_cmpk_ge_u32 s99, 0xc0
	s_cselect_b32 s99, 4, 0
	s_or_b32 s98, s98, s99
	v_readfirstlane_b32 s99, v245
	s_cmpk_ge_u32 s99, 0xc0
	s_cselect_b32 s99, 8, 0
	s_or_b32 s98, s98, s99
	v_readfirstlane_b32 s99, v246
	s_cmpk_ge_u32 s99, 0xc0
	s_cselect_b32 s99, 16, 0
	s_or_b32 s98, s98, s99
	v_readfirstlane_b32 s99, v247
	s_cmpk_ge_u32 s99, 0xc0
	s_cselect_b32 s99, 32, 0
	s_or_b32 s98, s98, s99
	v_readfirstlane_b32 s99, v248
	s_cmpk_ge_u32 s99, 0xc0
	s_cselect_b32 s99, 64, 0
	s_or_b32 s98, s98, s99
	v_readfirstlane_b32 s99, v249
	s_cmpk_ge_u32 s99, 0xc0
	s_cselect_b32 s99, 128, 0
	s_or_b32 s98, s98, s99
.Lp4q_noprobe:
	s_lshr_b32 s99, s98, s38
	s_and_b32 s99, s99, 1
	s_cmp_eq_u32 s99, 0
	s_cbranch_scc1 .Lp4q_claim
	v_mov_b32_e32 v193, 0xc0
	s_branch .LBB0_1122
.Lp4q_claim:
	s_mov_b64 s[48:49], exec
	v_mbcnt_lo_u32_b32 v0, s48, 0
	v_mbcnt_hi_u32_b32 v0, s49, v0
	v_cmp_eq_u32_e32 vcc, 0, v0
	s_and_saveexec_b64 s[4:5], vcc
	s_cbranch_execz .LBB0_1121
	s_lshl_b32 s34, s38, 2
	s_bcnt1_i32_b64 s35, s[48:49]
	v_mov_b32_e32 v1, s34
	v_mov_b32_e32 v2, s35
	global_atomic_add v1, v1, v2, s[88:89] sc0

; __global__ void __launch_bounds__(NTHREADS) fwd_megakernel(Params p) {
;     ...
;   for (int st_ = 0; st_ < 8; ++st_) {
;     const int xq = (xcd + st_) & 7;
;     int pend = 0;
;     if (tid == 0) pend = (int)atomicAdd(&ctr[8 + xq], 1u);
.LBB0_2043:
	s_or_b64 exec, exec, s[2:3]
	s_mov_b32 s3, 0
	v_mov_b32_e32 v161, 0
	s_movk_i32 s26, 0x6c00
	s_movk_i32 s27, 0x110
	s_mov_b32 s2, 0x3e0293ee
	s_mov_b32 s28, 0x41000000
	s_mov_b64 s[10:11], 0x5ac0
	v_mov_b32_e32 v171, 0xff800000
	v_readlane_b32 s29, v241, 35
	s_mov_b32 s98, 0
	s_barrier
	s_branch .LBB0_2045

; __global__ void __launch_bounds__(NTHREADS) fwd_megakernel(Params p) {
;     ...
;   for (int st_ = 0; st_ < 8; ++st_) {
;     const int xq = (xcd + st_) & 7;
;     int pend = 0;
;     if (tid == 0) pend = (int)atomicAdd(&ctr[8 + xq], 1u);
;     for (;;) {
;       __syncthreads();
;       if (tid == 0) s_item = pend;
;       __syncthreads();
;       const int n = s_item;
;       if (n >= 64) break;
;       if (tid == 0) pend = (int)atomicAdd(&ctr[8 + xq], 1u);
.LBB0_2045:
	v_readlane_b32 s4, v241, 35
	s_add_i32 s4, s3, s4
	s_and_b32 s12, s4, 7
	v_mov_b32_e32 v172, v161
	s_and_saveexec_b64 s[4:5], s[0:1]
	s_cbranch_execz .LBB0_2049
	s_cmp_lg_u32 s3, 1
	s_cbranch_scc1 .Lfoxq_noprobe
	global_load_dword v242, v161, s[88:89] offset:32 sc0 sc1
	global_load_dword v243, v161, s[88:89] offset:36 sc0 sc1
	global_load_dword v244, v161, s[88:89] offset:40 sc0 sc1
	global_load_dword v245, v161, s[88:89] offset:44 sc0 sc1
	global_load_dword v246, v161, s[88:89] offset:48 sc0 sc1
	global_load_dword v247, v161, s[88:89] offset:52 sc0 sc1
	global_load_dword v248, v161, s[88:89] offset:56 sc0 sc1
	global_load_dword v249, v161, s[88:89] offset:60 sc0 sc1
	s_mov_b32 s98, 0
	s_waitcnt vmcnt(0)
	v_readfirstlane_b32 s99, v242
	s_cmpk_ge_u32 s99, 0x40
	s_cselect_b32 s99, 1, 0
	s_or_b32 s98, s98, s99
	v_readfirstlane_b32 s99, v243
	s_cmpk_ge_u32 s99, 0x40
	s_cselect_b32 s99, 2, 0
	s_or_b32 s98, s98, s99
	v_readfirstlane_b32 s99, v244
	s_cmpk_ge_u32 s99, 0x40
	s_cselect_b32 s99, 4, 0
	s_or_b32 s98, s98, s99
	v_readfirstlane_b32 s99, v245
	s_cmpk_ge_u32 s99, 0x40
	s_cselect_b32 s99, 8, 0
	s_or_b32 s98, s98, s99
	v_readfirstlane_b32 s99, v246
	s_cmpk_ge_u32 s99, 0x40
	s_cselect_b32 s99, 16, 0
	s_or_b32 s98, s98, s99
	v_readfirstlane_b32 s99, v247
	s_cmpk_ge_u32 s99, 0x40
	s_cselect_b32 s99, 32, 0
	s_or_b32 s98, s98, s99
	v_readfirstlane_b32 s99, v248
	s_cmpk_ge_u32 s99, 0x40
	s_cselect_b32 s99, 64, 0
	s_or_b32 s98, s98, s99
	v_readfirstlane_b32 s99, v249
	s_cmpk_ge_u32 s99, 0x40
	s_cselect_b32 s99, 128, 0
	s_or_b32 s98, s98, s99
.Lfoxq_noprobe:
	s_lshr_b32 s99, s98, s12
	s_and_b32 s99, s99, 1
	s_cmp_eq_u32 s99, 0
	s_cbranch_scc1 .Lfoxq_claim
	v_mov_b32_e32 v172, 0x40
	s_branch .LBB0_2049
.Lfoxq_claim:
	s_mov_b64 s[8:9], exec
	v_mbcnt_lo_u32_b32 v0, s8, 0
	v_mbcnt_hi_u32_b32 v0, s9, v0
	v_cmp_eq_u32_e32 vcc, 0, v0
	s_and_saveexec_b64 s[6:7], vcc
	s_cbranch_execz .LBB0_2048
	s_lshl_b32 s13, s12, 2
	s_bcnt1_i32_b64 s8, s[8:9]
	v_mov_b32_e32 v1, s13
	v_mov_b32_e32 v2, s8
	global_atomic_add v1, v1, v2, s[88:89] offset:32 sc0

; __global__ void __launch_bounds__(NTHREADS) fwd_megakernel(Params p) {
	.amdhsa_kernel _Z14fwd_megakernel6Params
		.amdhsa_group_segment_fixed_size 16
		.amdhsa_private_segment_fixed_size 0
		.amdhsa_kernarg_size 392
		.amdhsa_user_sgpr_count 2
		.amdhsa_user_sgpr_dispatch_ptr 0
		.amdhsa_user_sgpr_queue_ptr 0
		.amdhsa_user_sgpr_kernarg_segment_ptr 1
		.amdhsa_user_sgpr_dispatch_id 0
		.amdhsa_user_sgpr_kernarg_preload_length 0
		.amdhsa_user_sgpr_kernarg_preload_offset 0
		.amdhsa_user_sgpr_private_segment_size 0
		.amdhsa_uses_dynamic_stack 0
		.amdhsa_enable_private_segment 0
		.amdhsa_system_sgpr_workgroup_id_x 1
		.amdhsa_system_sgpr_workgroup_id_y 0
		.amdhsa_system_sgpr_workgroup_id_z 0
		.amdhsa_system_sgpr_workgroup_info 0
		.amdhsa_system_vgpr_workitem_id 2
		.amdhsa_next_free_vgpr 256
		.amdhsa_next_free_sgpr 100
		.amdhsa_accum_offset 256
		.amdhsa_reserve_vcc 1
		.amdhsa_float_round_mode_32 0
		.amdhsa_float_round_mode_16_64 0
		.amdhsa_float_denorm_mode_32 3
		.amdhsa_float_denorm_mode_16_64 3
		.amdhsa_dx10_clamp 1
		.amdhsa_ieee_mode 1
		.amdhsa_fp16_overflow 0
		.amdhsa_tg_split 0
		.amdhsa_exception_fp_ieee_invalid_op 0
		.amdhsa_exception_fp_denorm_src 0
		.amdhsa_exception_fp_ieee_div_zero 0
		.amdhsa_exception_fp_ieee_overflow 0
		.amdhsa_exception_fp_ieee_underflow 0
		.amdhsa_exception_fp_ieee_inexact 0
		.amdhsa_exception_int_div_zero 0
	.end_amdhsa_kernel

; __global__ void __launch_bounds__(NTHREADS) fwd_megakernel(Params p) {
amdhsa.kernels:
  - .agpr_count:     0
    .args:
      - .offset:         0
        .size:           136
        .value_kind:     by_value
      - .offset:         136
        .size:           4
        .value_kind:     hidden_block_count_x
      - .offset:         140
        .size:           4
        .value_kind:     hidden_block_count_y
      - .offset:         144
        .size:           4
        .value_kind:     hidden_block_count_z
      - .offset:         148
        .size:           2
        .value_kind:     hidden_group_size_x
      - .offset:         150
        .size:           2
        .value_kind:     hidden_group_size_y
      - .offset:         152
        .size:           2
        .value_kind:     hidden_group_size_z
      - .offset:         154
        .size:           2
        .value_kind:     hidden_remainder_x
      - .offset:         156
        .size:           2
        .value_kind:     hidden_remainder_y
      - .offset:         158
        .size:           2
        .value_kind:     hidden_remainder_z
      - .offset:         176
        .size:           8
        .value_kind:     hidden_global_offset_x
      - .offset:         184
        .size:           8
        .value_kind:     hidden_global_offset_y
      - .offset:         192
        .size:           8
        .value_kind:     hidden_global_offset_z
      - .offset:         200
        .size:           2
        .value_kind:     hidden_grid_dims
      - .offset:         224
        .size:           8
        .value_kind:     hidden_multigrid_sync_arg
      - .offset:         256
        .size:           4
        .value_kind:     hidden_dynamic_lds_size
    .group_segment_fixed_size: 16
    .kernarg_segment_align: 8
    .kernarg_segment_size: 392
    .language:       OpenCL C
    .language_version:
      - 2
      - 0
    .max_flat_workgroup_size: 512
    .name:           _Z14fwd_megakernel6Params
    .private_segment_fixed_size: 0
    .sgpr_count:     106
    .sgpr_spill_count: 130
    .symbol:         _Z14fwd_megakernel6Params.kd
    .uniform_work_group_size: 1
    .uses_dynamic_stack: false
    .vgpr_count:     256
    .vgpr_spill_count: 0
    .wavefront_size: 64
